# phase 0: x f32 -> bf16 rows + rstd pass hand-written with the same rolling 4-row pipeline / DPP wave sum
# baseline (speedup 1.0000x reference)
; #define PIN(i) karg_ptr(8 * (i))
; __device__ __forceinline__ float wave_sum(float v) {
; #pragma unroll
;     for (int o = 1; o < 64; o <<= 1) v += __shfl_xor(v, o);
;     return v;
; __global__ void __launch_bounds__(512, 2) fwd_megakernel(Params P) {
;     ...
;         for (int row0 = gw; row0 < MTOK; row0 += 4 * NGW) {
;             f32x4 xa[4][2][2];
; #pragma unroll
;             for (int k = 0; k < 4; ++k) { const int row = row0 + k * NGW; const float* xr = row < 16384 ? PIN(I_XP) + (size_t)row * DM : PIN(I_XS) + (size_t)(row - 16384) * DM;
; #pragma unroll
;                 for (int j = 0; j < 2; ++j) { xa[k][j][0] = *(const f32x4*)(xr + 8 * lane + 512 * j); xa[k][j][1] = *(const f32x4*)(xr + 8 * lane + 512 * j + 4); } }
; #pragma unroll
;             for (int k = 0; k < 4; ++k) { const int row = row0 + k * NGW; float s = 0.f;
; #pragma unroll
;                 for (int j = 0; j < 2; ++j) { const f32x4 a = xa[k][j][0], b = xa[k][j][1];
;                     s += (a[0] * a[0] + a[1] * a[1]) + (a[2] * a[2] + a[3] * a[3]) + (b[0] * b[0] + b[1] * b[1]) + (b[2] * b[2] + b[3] * b[3]);
;                     u32x4 o; o.x = pk2(a[0], a[1]); o.y = pk2(a[2], a[3]); o.z = pk2(b[0], b[1]); o.w = pk2(b[2], b[3]); *(u32x4*)(XB + (size_t)row * DM + 8 * lane + 512 * j) = o; }
;                 s = wave_sum(s); if (lane == 0) rstdA[row] = __builtin_amdgcn_rsqf(s * (1.0f / DM) + RMS_EPS); }
.LBB0_54:
	v_lshrrev_b32_e32 v1, 6, v0
	v_readlane_b32 s4, v255, 4
	s_nop 1
	v_add_u32_e32 v66, s4, v1
	s_mov_b32 s4, 0x8000
	v_cmp_gt_i32_e32 vcc, s4, v66
	s_and_saveexec_b64 s[6:7], vcc
	s_mov_b32 s62, s94
	s_cbranch_execz .LBB0_81
	v_lshrrev_b32_e32 v22, 6, v0
	v_readlane_b32 s17, v255, 4
	s_load_dwordx2 s[4:5], s[0:1], 0x98
	s_load_dwordx2 s[8:9], s[0:1], 0x0
	s_load_dwordx2 s[10:11], s[0:1], 0x8
	v_readfirstlane_b32 s18, v22
	v_and_b32_e32 v22, 63, v0
	v_mov_b32_e32 v92, 0x358637bd
	s_add_i32 s17, s17, s18
	s_bfm_b64 s[12:13], 1, 63
	s_lshl_b32 s18, s17, 12
	v_lshl_add_u32 v18, v22, 5, s18
	s_lshl_b32 s18, s17, 11
	v_lshl_add_u32 v19, v22, 4, s18
	s_lshl_b32 s18, s17, 2
	v_mov_b32_e32 v20, s18
	s_waitcnt lgkmcnt(0)
	global_load_dwordx4 v[24:27], v18, s[8:9]
	global_load_dwordx4 v[28:31], v18, s[8:9] offset:16
	global_load_dwordx4 v[32:35], v18, s[8:9] offset:2048
	global_load_dwordx4 v[36:39], v18, s[8:9] offset:2064
	v_add_u32_e32 v18, 0x800000, v18
	global_load_dwordx4 v[40:43], v18, s[8:9]
	global_load_dwordx4 v[44:47], v18, s[8:9] offset:16
	global_load_dwordx4 v[48:51], v18, s[8:9] offset:2048
	global_load_dwordx4 v[52:55], v18, s[8:9] offset:2064
	v_add_u32_e32 v18, 0x800000, v18
	global_load_dwordx4 v[56:59], v18, s[8:9]
	global_load_dwordx4 v[60:63], v18, s[8:9] offset:16
	global_load_dwordx4 v[64:67], v18, s[8:9] offset:2048
	global_load_dwordx4 v[68:71], v18, s[8:9] offset:2064
	v_add_u32_e32 v18, 0x800000, v18
	global_load_dwordx4 v[72:75], v18, s[8:9]
	global_load_dwordx4 v[76:79], v18, s[8:9] offset:16
	global_load_dwordx4 v[80:83], v18, s[8:9] offset:2048
	global_load_dwordx4 v[84:87], v18, s[8:9] offset:2064
	s_waitcnt vmcnt(12)
	v_pk_mul_f32 v[88:89], v[24:25], v[24:25]
	v_pk_fma_f32 v[88:89], v[26:27], v[26:27], v[88:89]
	v_pk_fma_f32 v[88:89], v[28:29], v[28:29], v[88:89]
	v_pk_fma_f32 v[88:89], v[30:31], v[30:31], v[88:89]
	v_pk_fma_f32 v[88:89], v[32:33], v[32:33], v[88:89]
	v_pk_fma_f32 v[88:89], v[34:35], v[34:35], v[88:89]
	v_pk_fma_f32 v[88:89], v[36:37], v[36:37], v[88:89]
	v_pk_fma_f32 v[88:89], v[38:39], v[38:39], v[88:89]
	v_add_u32_e32 v19, 0x3001000, v19
	v_cvt_pk_bf16_f32 v24, v24, v25
	v_cvt_pk_bf16_f32 v25, v26, v27
	v_cvt_pk_bf16_f32 v26, v28, v29
	v_cvt_pk_bf16_f32 v27, v30, v31
	global_store_dwordx4 v19, v[24:27], s[4:5]
	v_cvt_pk_bf16_f32 v32, v32, v33
	v_cvt_pk_bf16_f32 v33, v34, v35
	v_cvt_pk_bf16_f32 v34, v36, v37
	v_cvt_pk_bf16_f32 v35, v38, v39
	global_store_dwordx4 v19, v[32:35], s[4:5] offset:1024
	v_add_f32_e32 v90, v88, v89
	v_add_u32_e32 v20, 0x2d00000, v20
	s_nop 1
	v_add_f32_dpp v90, v90, v90 quad_perm:[1,0,3,2] row_mask:0xf bank_mask:0xf
	s_nop 1
	v_add_f32_dpp v90, v90, v90 quad_perm:[2,3,0,1] row_mask:0xf bank_mask:0xf
	s_nop 1
	v_add_f32_dpp v90, v90, v90 row_half_mirror row_mask:0xf bank_mask:0xf
	s_nop 1
	v_add_f32_dpp v90, v90, v90 row_mirror row_mask:0xf bank_mask:0xf
	s_nop 1
	v_add_f32_dpp v90, v90, v90 row_bcast:15 row_mask:0xa bank_mask:0xf
	s_nop 1
	v_add_f32_dpp v90, v90, v90 row_bcast:31 row_mask:0xc bank_mask:0xf
	v_fmamk_f32 v91, v90, 0x3a800000, v92
	v_rsq_f32_e32 v91, v91
	s_mov_b64 exec, s[12:13]
	global_store_dword v20, v91, s[4:5]
	s_mov_b64 exec, -1
	v_add_u32_e32 v18, 0x800000, v18
	global_load_dwordx4 v[24:27], v18, s[8:9]
	global_load_dwordx4 v[28:31], v18, s[8:9] offset:16
	global_load_dwordx4 v[32:35], v18, s[8:9] offset:2048
	global_load_dwordx4 v[36:39], v18, s[8:9] offset:2064
	s_waitcnt vmcnt(15)
	v_pk_mul_f32 v[88:89], v[40:41], v[40:41]
	v_pk_fma_f32 v[88:89], v[42:43], v[42:43], v[88:89]
	v_pk_fma_f32 v[88:89], v[44:45], v[44:45], v[88:89]
	v_pk_fma_f32 v[88:89], v[46:47], v[46:47], v[88:89]
	v_pk_fma_f32 v[88:89], v[48:49], v[48:49], v[88:89]
	v_pk_fma_f32 v[88:89], v[50:51], v[50:51], v[88:89]
	v_pk_fma_f32 v[88:89], v[52:53], v[52:53], v[88:89]
	v_pk_fma_f32 v[88:89], v[54:55], v[54:55], v[88:89]
	v_add_u32_e32 v19, 0x400000, v19
	v_cvt_pk_bf16_f32 v40, v40, v41
	v_cvt_pk_bf16_f32 v41, v42, v43
	v_cvt_pk_bf16_f32 v42, v44, v45
	v_cvt_pk_bf16_f32 v43, v46, v47
	global_store_dwordx4 v19, v[40:43], s[4:5]
	v_cvt_pk_bf16_f32 v48, v48, v49
	v_cvt_pk_bf16_f32 v49, v50, v51
	v_cvt_pk_bf16_f32 v50, v52, v53
	v_cvt_pk_bf16_f32 v51, v54, v55
	global_store_dwordx4 v19, v[48:51], s[4:5] offset:1024
	v_add_f32_e32 v90, v88, v89
	v_add_u32_e32 v20, 0x2000, v20
	s_nop 1
	v_add_f32_dpp v90, v90, v90 quad_perm:[1,0,3,2] row_mask:0xf bank_mask:0xf
	s_nop 1
	v_add_f32_dpp v90, v90, v90 quad_perm:[2,3,0,1] row_mask:0xf bank_mask:0xf
	s_nop 1
	v_add_f32_dpp v90, v90, v90 row_half_mirror row_mask:0xf bank_mask:0xf
	s_nop 1
	v_add_f32_dpp v90, v90, v90 row_mirror row_mask:0xf bank_mask:0xf
	s_nop 1
	v_add_f32_dpp v90, v90, v90 row_bcast:15 row_mask:0xa bank_mask:0xf
	s_nop 1
	v_add_f32_dpp v90, v90, v90 row_bcast:31 row_mask:0xc bank_mask:0xf
	v_fmamk_f32 v91, v90, 0x3a800000, v92
	v_rsq_f32_e32 v91, v91
	s_mov_b64 exec, s[12:13]
	global_store_dword v20, v91, s[4:5]
	s_mov_b64 exec, -1
	v_add_u32_e32 v18, 0x800000, v18
	global_load_dwordx4 v[40:43], v18, s[8:9]
	global_load_dwordx4 v[44:47], v18, s[8:9] offset:16
	global_load_dwordx4 v[48:51], v18, s[8:9] offset:2048
	global_load_dwordx4 v[52:55], v18, s[8:9] offset:2064
	s_waitcnt vmcnt(18)
; #define PIN(i) karg_ptr(8 * (i))
; __global__ void __launch_bounds__(512, 2) fwd_megakernel(Params P) {
;     ...
;         for (int row0 = gw; row0 < MTOK; row0 += 4 * NGW) {
;             f32x4 xa[4][2][2];
; #pragma unroll
;             for (int k = 0; k < 4; ++k) { const int row = row0 + k * NGW; const float* xr = row < 16384 ? PIN(I_XP) + (size_t)row * DM : PIN(I_XS) + (size_t)(row - 16384) * DM;
; #pragma unroll
;                 for (int j = 0; j < 2; ++j) { xa[k][j][0] = *(const f32x4*)(xr + 8 * lane + 512 * j); xa[k][j][1] = *(const f32x4*)(xr + 8 * lane + 512 * j + 4); } }
; #pragma unroll
;             for (int k = 0; k < 4; ++k) { const int row = row0 + k * NGW; float s = 0.f;
; #pragma unroll
;                 for (int j = 0; j < 2; ++j) { const f32x4 a = xa[k][j][0], b = xa[k][j][1];
;                     s += (a[0] * a[0] + a[1] * a[1]) + (a[2] * a[2] + a[3] * a[3]) + (b[0] * b[0] + b[1] * b[1]) + (b[2] * b[2] + b[3] * b[3]);
;                     u32x4 o; o.x = pk2(a[0], a[1]); o.y = pk2(a[2], a[3]); o.z = pk2(b[0], b[1]); o.w = pk2(b[2], b[3]); *(u32x4*)(XB + (size_t)row * DM + 8 * lane + 512 * j) = o; }
;                 s = wave_sum(s); if (lane == 0) rstdA[row] = __builtin_amdgcn_rsqf(s * (1.0f / DM) + RMS_EPS); }
	v_pk_mul_f32 v[88:89], v[56:57], v[56:57]
	v_pk_fma_f32 v[88:89], v[58:59], v[58:59], v[88:89]
	v_pk_fma_f32 v[88:89], v[60:61], v[60:61], v[88:89]
	v_pk_fma_f32 v[88:89], v[62:63], v[62:63], v[88:89]
	v_pk_fma_f32 v[88:89], v[64:65], v[64:65], v[88:89]
	v_pk_fma_f32 v[88:89], v[66:67], v[66:67], v[88:89]
	v_pk_fma_f32 v[88:89], v[68:69], v[68:69], v[88:89]
	v_pk_fma_f32 v[88:89], v[70:71], v[70:71], v[88:89]
	v_add_u32_e32 v19, 0x400000, v19
	v_cvt_pk_bf16_f32 v56, v56, v57
	v_cvt_pk_bf16_f32 v57, v58, v59
	v_cvt_pk_bf16_f32 v58, v60, v61
	v_cvt_pk_bf16_f32 v59, v62, v63
	global_store_dwordx4 v19, v[56:59], s[4:5]
	v_cvt_pk_bf16_f32 v64, v64, v65
	v_cvt_pk_bf16_f32 v65, v66, v67
	v_cvt_pk_bf16_f32 v66, v68, v69
	v_cvt_pk_bf16_f32 v67, v70, v71
	global_store_dwordx4 v19, v[64:67], s[4:5] offset:1024
	v_add_f32_e32 v90, v88, v89
	v_add_u32_e32 v20, 0x2000, v20
	s_nop 1
	v_add_f32_dpp v90, v90, v90 quad_perm:[1,0,3,2] row_mask:0xf bank_mask:0xf
	s_nop 1
	v_add_f32_dpp v90, v90, v90 quad_perm:[2,3,0,1] row_mask:0xf bank_mask:0xf
	s_nop 1
	v_add_f32_dpp v90, v90, v90 row_half_mirror row_mask:0xf bank_mask:0xf
	s_nop 1
	v_add_f32_dpp v90, v90, v90 row_mirror row_mask:0xf bank_mask:0xf
	s_nop 1
	v_add_f32_dpp v90, v90, v90 row_bcast:15 row_mask:0xa bank_mask:0xf
	s_nop 1
	v_add_f32_dpp v90, v90, v90 row_bcast:31 row_mask:0xc bank_mask:0xf
	v_fmamk_f32 v91, v90, 0x3a800000, v92
	v_rsq_f32_e32 v91, v91
	s_mov_b64 exec, s[12:13]
	global_store_dword v20, v91, s[4:5]
	s_mov_b64 exec, -1
	v_add_u32_e32 v18, 0x800000, v18
	global_load_dwordx4 v[56:59], v18, s[8:9]
	global_load_dwordx4 v[60:63], v18, s[8:9] offset:16
	global_load_dwordx4 v[64:67], v18, s[8:9] offset:2048
	global_load_dwordx4 v[68:71], v18, s[8:9] offset:2064
	s_waitcnt vmcnt(21)
	v_pk_mul_f32 v[88:89], v[72:73], v[72:73]
	v_pk_fma_f32 v[88:89], v[74:75], v[74:75], v[88:89]
	v_pk_fma_f32 v[88:89], v[76:77], v[76:77], v[88:89]
	v_pk_fma_f32 v[88:89], v[78:79], v[78:79], v[88:89]
	v_pk_fma_f32 v[88:89], v[80:81], v[80:81], v[88:89]
	v_pk_fma_f32 v[88:89], v[82:83], v[82:83], v[88:89]
	v_pk_fma_f32 v[88:89], v[84:85], v[84:85], v[88:89]
	v_pk_fma_f32 v[88:89], v[86:87], v[86:87], v[88:89]
	v_add_u32_e32 v19, 0x400000, v19
	v_cvt_pk_bf16_f32 v72, v72, v73
	v_cvt_pk_bf16_f32 v73, v74, v75
	v_cvt_pk_bf16_f32 v74, v76, v77
	v_cvt_pk_bf16_f32 v75, v78, v79
	global_store_dwordx4 v19, v[72:75], s[4:5]
	v_cvt_pk_bf16_f32 v80, v80, v81
	v_cvt_pk_bf16_f32 v81, v82, v83
	v_cvt_pk_bf16_f32 v82, v84, v85
	v_cvt_pk_bf16_f32 v83, v86, v87
	global_store_dwordx4 v19, v[80:83], s[4:5] offset:1024
	v_add_f32_e32 v90, v88, v89
	v_add_u32_e32 v20, 0x2000, v20
	s_nop 1
	v_add_f32_dpp v90, v90, v90 quad_perm:[1,0,3,2] row_mask:0xf bank_mask:0xf
	s_nop 1
	v_add_f32_dpp v90, v90, v90 quad_perm:[2,3,0,1] row_mask:0xf bank_mask:0xf
	s_nop 1
	v_add_f32_dpp v90, v90, v90 row_half_mirror row_mask:0xf bank_mask:0xf
	s_nop 1
	v_add_f32_dpp v90, v90, v90 row_mirror row_mask:0xf bank_mask:0xf
	s_nop 1
	v_add_f32_dpp v90, v90, v90 row_bcast:15 row_mask:0xa bank_mask:0xf
	s_nop 1
	v_add_f32_dpp v90, v90, v90 row_bcast:31 row_mask:0xc bank_mask:0xf
	v_fmamk_f32 v91, v90, 0x3a800000, v92
	v_rsq_f32_e32 v91, v91
	s_mov_b64 exec, s[12:13]
	global_store_dword v20, v91, s[4:5]
	s_mov_b64 exec, -1
	v_add_u32_e32 v18, 0x800000, v18
	global_load_dwordx4 v[72:75], v18, s[8:9]
	global_load_dwordx4 v[76:79], v18, s[8:9] offset:16
	global_load_dwordx4 v[80:83], v18, s[8:9] offset:2048
	global_load_dwordx4 v[84:87], v18, s[8:9] offset:2064
	s_waitcnt vmcnt(21)
	v_pk_mul_f32 v[88:89], v[24:25], v[24:25]
	v_pk_fma_f32 v[88:89], v[26:27], v[26:27], v[88:89]
	v_pk_fma_f32 v[88:89], v[28:29], v[28:29], v[88:89]
	v_pk_fma_f32 v[88:89], v[30:31], v[30:31], v[88:89]
	v_pk_fma_f32 v[88:89], v[32:33], v[32:33], v[88:89]
	v_pk_fma_f32 v[88:89], v[34:35], v[34:35], v[88:89]
	v_pk_fma_f32 v[88:89], v[36:37], v[36:37], v[88:89]
	v_pk_fma_f32 v[88:89], v[38:39], v[38:39], v[88:89]
	v_add_u32_e32 v19, 0x400000, v19
	v_cvt_pk_bf16_f32 v24, v24, v25
	v_cvt_pk_bf16_f32 v25, v26, v27
	v_cvt_pk_bf16_f32 v26, v28, v29
	v_cvt_pk_bf16_f32 v27, v30, v31
	global_store_dwordx4 v19, v[24:27], s[4:5]
	v_cvt_pk_bf16_f32 v32, v32, v33
	v_cvt_pk_bf16_f32 v33, v34, v35
	v_cvt_pk_bf16_f32 v34, v36, v37
	v_cvt_pk_bf16_f32 v35, v38, v39
	global_store_dwordx4 v19, v[32:35], s[4:5] offset:1024
	v_add_f32_e32 v90, v88, v89
	v_add_u32_e32 v20, 0x2000, v20
	s_nop 1
	v_add_f32_dpp v90, v90, v90 quad_perm:[1,0,3,2] row_mask:0xf bank_mask:0xf
	s_nop 1
	v_add_f32_dpp v90, v90, v90 quad_perm:[2,3,0,1] row_mask:0xf bank_mask:0xf
	s_nop 1
	v_add_f32_dpp v90, v90, v90 row_half_mirror row_mask:0xf bank_mask:0xf
	s_nop 1
	v_add_f32_dpp v90, v90, v90 row_mirror row_mask:0xf bank_mask:0xf
	s_nop 1
	v_add_f32_dpp v90, v90, v90 row_bcast:15 row_mask:0xa bank_mask:0xf
	s_nop 1
	v_add_f32_dpp v90, v90, v90 row_bcast:31 row_mask:0xc bank_mask:0xf
	v_fmamk_f32 v91, v90, 0x3a800000, v92
	v_rsq_f32_e32 v91, v91
	s_mov_b64 exec, s[12:13]
	global_store_dword v20, v91, s[4:5]
	s_mov_b64 exec, -1
	v_add_u32_e32 v18, 0xfc800000, v18
	global_load_dwordx4 v[24:27], v18, s[10:11]
	global_load_dwordx4 v[28:31], v18, s[10:11] offset:16
	global_load_dwordx4 v[32:35], v18, s[10:11] offset:2048
	global_load_dwordx4 v[36:39], v18, s[10:11] offset:2064
	s_waitcnt vmcnt(21)
; #define PIN(i) karg_ptr(8 * (i))
; __global__ void __launch_bounds__(512, 2) fwd_megakernel(Params P) {
;     ...
;         for (int row0 = gw; row0 < MTOK; row0 += 4 * NGW) {
;             f32x4 xa[4][2][2];
; #pragma unroll
;             for (int k = 0; k < 4; ++k) { const int row = row0 + k * NGW; const float* xr = row < 16384 ? PIN(I_XP) + (size_t)row * DM : PIN(I_XS) + (size_t)(row - 16384) * DM;
; #pragma unroll
;                 for (int j = 0; j < 2; ++j) { xa[k][j][0] = *(const f32x4*)(xr + 8 * lane + 512 * j); xa[k][j][1] = *(const f32x4*)(xr + 8 * lane + 512 * j + 4); } }
; #pragma unroll
;             for (int k = 0; k < 4; ++k) { const int row = row0 + k * NGW; float s = 0.f;
; #pragma unroll
;                 for (int j = 0; j < 2; ++j) { const f32x4 a = xa[k][j][0], b = xa[k][j][1];
;                     s += (a[0] * a[0] + a[1] * a[1]) + (a[2] * a[2] + a[3] * a[3]) + (b[0] * b[0] + b[1] * b[1]) + (b[2] * b[2] + b[3] * b[3]);
;                     u32x4 o; o.x = pk2(a[0], a[1]); o.y = pk2(a[2], a[3]); o.z = pk2(b[0], b[1]); o.w = pk2(b[2], b[3]); *(u32x4*)(XB + (size_t)row * DM + 8 * lane + 512 * j) = o; }
;                 s = wave_sum(s); if (lane == 0) rstdA[row] = __builtin_amdgcn_rsqf(s * (1.0f / DM) + RMS_EPS); }
	v_pk_mul_f32 v[88:89], v[40:41], v[40:41]
	v_pk_fma_f32 v[88:89], v[42:43], v[42:43], v[88:89]
	v_pk_fma_f32 v[88:89], v[44:45], v[44:45], v[88:89]
	v_pk_fma_f32 v[88:89], v[46:47], v[46:47], v[88:89]
	v_pk_fma_f32 v[88:89], v[48:49], v[48:49], v[88:89]
	v_pk_fma_f32 v[88:89], v[50:51], v[50:51], v[88:89]
	v_pk_fma_f32 v[88:89], v[52:53], v[52:53], v[88:89]
	v_pk_fma_f32 v[88:89], v[54:55], v[54:55], v[88:89]
	v_add_u32_e32 v19, 0x400000, v19
	v_cvt_pk_bf16_f32 v40, v40, v41
	v_cvt_pk_bf16_f32 v41, v42, v43
	v_cvt_pk_bf16_f32 v42, v44, v45
	v_cvt_pk_bf16_f32 v43, v46, v47
	global_store_dwordx4 v19, v[40:43], s[4:5]
	v_cvt_pk_bf16_f32 v48, v48, v49
	v_cvt_pk_bf16_f32 v49, v50, v51
	v_cvt_pk_bf16_f32 v50, v52, v53
	v_cvt_pk_bf16_f32 v51, v54, v55
	global_store_dwordx4 v19, v[48:51], s[4:5] offset:1024
	v_add_f32_e32 v90, v88, v89
	v_add_u32_e32 v20, 0x2000, v20
	s_nop 1
	v_add_f32_dpp v90, v90, v90 quad_perm:[1,0,3,2] row_mask:0xf bank_mask:0xf
	s_nop 1
	v_add_f32_dpp v90, v90, v90 quad_perm:[2,3,0,1] row_mask:0xf bank_mask:0xf
	s_nop 1
	v_add_f32_dpp v90, v90, v90 row_half_mirror row_mask:0xf bank_mask:0xf
	s_nop 1
	v_add_f32_dpp v90, v90, v90 row_mirror row_mask:0xf bank_mask:0xf
	s_nop 1
	v_add_f32_dpp v90, v90, v90 row_bcast:15 row_mask:0xa bank_mask:0xf
	s_nop 1
	v_add_f32_dpp v90, v90, v90 row_bcast:31 row_mask:0xc bank_mask:0xf
	v_fmamk_f32 v91, v90, 0x3a800000, v92
	v_rsq_f32_e32 v91, v91
	s_mov_b64 exec, s[12:13]
	global_store_dword v20, v91, s[4:5]
	s_mov_b64 exec, -1
	v_add_u32_e32 v18, 0x800000, v18
	global_load_dwordx4 v[40:43], v18, s[10:11]
	global_load_dwordx4 v[44:47], v18, s[10:11] offset:16
	global_load_dwordx4 v[48:51], v18, s[10:11] offset:2048
	global_load_dwordx4 v[52:55], v18, s[10:11] offset:2064
	s_waitcnt vmcnt(21)
	v_pk_mul_f32 v[88:89], v[56:57], v[56:57]
	v_pk_fma_f32 v[88:89], v[58:59], v[58:59], v[88:89]
	v_pk_fma_f32 v[88:89], v[60:61], v[60:61], v[88:89]
	v_pk_fma_f32 v[88:89], v[62:63], v[62:63], v[88:89]
	v_pk_fma_f32 v[88:89], v[64:65], v[64:65], v[88:89]
	v_pk_fma_f32 v[88:89], v[66:67], v[66:67], v[88:89]
	v_pk_fma_f32 v[88:89], v[68:69], v[68:69], v[88:89]
	v_pk_fma_f32 v[88:89], v[70:71], v[70:71], v[88:89]
	v_add_u32_e32 v19, 0x400000, v19
	v_cvt_pk_bf16_f32 v56, v56, v57
	v_cvt_pk_bf16_f32 v57, v58, v59
	v_cvt_pk_bf16_f32 v58, v60, v61
	v_cvt_pk_bf16_f32 v59, v62, v63
	global_store_dwordx4 v19, v[56:59], s[4:5]
	v_cvt_pk_bf16_f32 v64, v64, v65
	v_cvt_pk_bf16_f32 v65, v66, v67
	v_cvt_pk_bf16_f32 v66, v68, v69
	v_cvt_pk_bf16_f32 v67, v70, v71
	global_store_dwordx4 v19, v[64:67], s[4:5] offset:1024
	v_add_f32_e32 v90, v88, v89
	v_add_u32_e32 v20, 0x2000, v20
	s_nop 1
	v_add_f32_dpp v90, v90, v90 quad_perm:[1,0,3,2] row_mask:0xf bank_mask:0xf
	s_nop 1
	v_add_f32_dpp v90, v90, v90 quad_perm:[2,3,0,1] row_mask:0xf bank_mask:0xf
	s_nop 1
	v_add_f32_dpp v90, v90, v90 row_half_mirror row_mask:0xf bank_mask:0xf
	s_nop 1
	v_add_f32_dpp v90, v90, v90 row_mirror row_mask:0xf bank_mask:0xf
	s_nop 1
	v_add_f32_dpp v90, v90, v90 row_bcast:15 row_mask:0xa bank_mask:0xf
	s_nop 1
	v_add_f32_dpp v90, v90, v90 row_bcast:31 row_mask:0xc bank_mask:0xf
	v_fmamk_f32 v91, v90, 0x3a800000, v92
	v_rsq_f32_e32 v91, v91
	s_mov_b64 exec, s[12:13]
	global_store_dword v20, v91, s[4:5]
	s_mov_b64 exec, -1
	v_add_u32_e32 v18, 0x800000, v18
	global_load_dwordx4 v[56:59], v18, s[10:11]
	global_load_dwordx4 v[60:63], v18, s[10:11] offset:16
	global_load_dwordx4 v[64:67], v18, s[10:11] offset:2048
	global_load_dwordx4 v[68:71], v18, s[10:11] offset:2064
	s_waitcnt vmcnt(21)
	v_pk_mul_f32 v[88:89], v[72:73], v[72:73]
	v_pk_fma_f32 v[88:89], v[74:75], v[74:75], v[88:89]
	v_pk_fma_f32 v[88:89], v[76:77], v[76:77], v[88:89]
	v_pk_fma_f32 v[88:89], v[78:79], v[78:79], v[88:89]
	v_pk_fma_f32 v[88:89], v[80:81], v[80:81], v[88:89]
	v_pk_fma_f32 v[88:89], v[82:83], v[82:83], v[88:89]
	v_pk_fma_f32 v[88:89], v[84:85], v[84:85], v[88:89]
	v_pk_fma_f32 v[88:89], v[86:87], v[86:87], v[88:89]
	v_add_u32_e32 v19, 0x400000, v19
	v_cvt_pk_bf16_f32 v72, v72, v73
	v_cvt_pk_bf16_f32 v73, v74, v75
	v_cvt_pk_bf16_f32 v74, v76, v77
	v_cvt_pk_bf16_f32 v75, v78, v79
	global_store_dwordx4 v19, v[72:75], s[4:5]
	v_cvt_pk_bf16_f32 v80, v80, v81
	v_cvt_pk_bf16_f32 v81, v82, v83
	v_cvt_pk_bf16_f32 v82, v84, v85
	v_cvt_pk_bf16_f32 v83, v86, v87
	global_store_dwordx4 v19, v[80:83], s[4:5] offset:1024
	v_add_f32_e32 v90, v88, v89
	v_add_u32_e32 v20, 0x2000, v20
	s_nop 1
	v_add_f32_dpp v90, v90, v90 quad_perm:[1,0,3,2] row_mask:0xf bank_mask:0xf
	s_nop 1
	v_add_f32_dpp v90, v90, v90 quad_perm:[2,3,0,1] row_mask:0xf bank_mask:0xf
	s_nop 1
	v_add_f32_dpp v90, v90, v90 row_half_mirror row_mask:0xf bank_mask:0xf
	s_nop 1
	v_add_f32_dpp v90, v90, v90 row_mirror row_mask:0xf bank_mask:0xf
	s_nop 1
	v_add_f32_dpp v90, v90, v90 row_bcast:15 row_mask:0xa bank_mask:0xf
	s_nop 1
	v_add_f32_dpp v90, v90, v90 row_bcast:31 row_mask:0xc bank_mask:0xf
	v_fmamk_f32 v91, v90, 0x3a800000, v92
	v_rsq_f32_e32 v91, v91
	s_mov_b64 exec, s[12:13]
	global_store_dword v20, v91, s[4:5]
	s_mov_b64 exec, -1
	v_add_u32_e32 v18, 0x800000, v18
	global_load_dwordx4 v[72:75], v18, s[10:11]
	global_load_dwordx4 v[76:79], v18, s[10:11] offset:16
	global_load_dwordx4 v[80:83], v18, s[10:11] offset:2048
	global_load_dwordx4 v[84:87], v18, s[10:11] offset:2064
	s_waitcnt vmcnt(21)
; #define PIN(i) karg_ptr(8 * (i))
; __global__ void __launch_bounds__(512, 2) fwd_megakernel(Params P) {
;     ...
;         for (int row0 = gw; row0 < MTOK; row0 += 4 * NGW) {
;             f32x4 xa[4][2][2];
; #pragma unroll
;             for (int k = 0; k < 4; ++k) { const int row = row0 + k * NGW; const float* xr = row < 16384 ? PIN(I_XP) + (size_t)row * DM : PIN(I_XS) + (size_t)(row - 16384) * DM;
; #pragma unroll
;                 for (int j = 0; j < 2; ++j) { xa[k][j][0] = *(const f32x4*)(xr + 8 * lane + 512 * j); xa[k][j][1] = *(const f32x4*)(xr + 8 * lane + 512 * j + 4); } }
; #pragma unroll
;             for (int k = 0; k < 4; ++k) { const int row = row0 + k * NGW; float s = 0.f;
; #pragma unroll
;                 for (int j = 0; j < 2; ++j) { const f32x4 a = xa[k][j][0], b = xa[k][j][1];
;                     s += (a[0] * a[0] + a[1] * a[1]) + (a[2] * a[2] + a[3] * a[3]) + (b[0] * b[0] + b[1] * b[1]) + (b[2] * b[2] + b[3] * b[3]);
;                     u32x4 o; o.x = pk2(a[0], a[1]); o.y = pk2(a[2], a[3]); o.z = pk2(b[0], b[1]); o.w = pk2(b[2], b[3]); *(u32x4*)(XB + (size_t)row * DM + 8 * lane + 512 * j) = o; }
;                 s = wave_sum(s); if (lane == 0) rstdA[row] = __builtin_amdgcn_rsqf(s * (1.0f / DM) + RMS_EPS); }
	v_pk_mul_f32 v[88:89], v[24:25], v[24:25]
	v_pk_fma_f32 v[88:89], v[26:27], v[26:27], v[88:89]
	v_pk_fma_f32 v[88:89], v[28:29], v[28:29], v[88:89]
	v_pk_fma_f32 v[88:89], v[30:31], v[30:31], v[88:89]
	v_pk_fma_f32 v[88:89], v[32:33], v[32:33], v[88:89]
	v_pk_fma_f32 v[88:89], v[34:35], v[34:35], v[88:89]
	v_pk_fma_f32 v[88:89], v[36:37], v[36:37], v[88:89]
	v_pk_fma_f32 v[88:89], v[38:39], v[38:39], v[88:89]
	v_add_u32_e32 v19, 0x400000, v19
	v_cvt_pk_bf16_f32 v24, v24, v25
	v_cvt_pk_bf16_f32 v25, v26, v27
	v_cvt_pk_bf16_f32 v26, v28, v29
	v_cvt_pk_bf16_f32 v27, v30, v31
	global_store_dwordx4 v19, v[24:27], s[4:5]
	v_cvt_pk_bf16_f32 v32, v32, v33
	v_cvt_pk_bf16_f32 v33, v34, v35
	v_cvt_pk_bf16_f32 v34, v36, v37
	v_cvt_pk_bf16_f32 v35, v38, v39
	global_store_dwordx4 v19, v[32:35], s[4:5] offset:1024
	v_add_f32_e32 v90, v88, v89
	v_add_u32_e32 v20, 0x2000, v20
	s_nop 1
	v_add_f32_dpp v90, v90, v90 quad_perm:[1,0,3,2] row_mask:0xf bank_mask:0xf
	s_nop 1
	v_add_f32_dpp v90, v90, v90 quad_perm:[2,3,0,1] row_mask:0xf bank_mask:0xf
	s_nop 1
	v_add_f32_dpp v90, v90, v90 row_half_mirror row_mask:0xf bank_mask:0xf
	s_nop 1
	v_add_f32_dpp v90, v90, v90 row_mirror row_mask:0xf bank_mask:0xf
	s_nop 1
	v_add_f32_dpp v90, v90, v90 row_bcast:15 row_mask:0xa bank_mask:0xf
	s_nop 1
	v_add_f32_dpp v90, v90, v90 row_bcast:31 row_mask:0xc bank_mask:0xf
	v_fmamk_f32 v91, v90, 0x3a800000, v92
	v_rsq_f32_e32 v91, v91
	s_mov_b64 exec, s[12:13]
	global_store_dword v20, v91, s[4:5]
	s_mov_b64 exec, -1
	v_add_u32_e32 v18, 0x800000, v18
	global_load_dwordx4 v[24:27], v18, s[10:11]
	global_load_dwordx4 v[28:31], v18, s[10:11] offset:16
	global_load_dwordx4 v[32:35], v18, s[10:11] offset:2048
	global_load_dwordx4 v[36:39], v18, s[10:11] offset:2064
	s_waitcnt vmcnt(21)
	v_pk_mul_f32 v[88:89], v[40:41], v[40:41]
	v_pk_fma_f32 v[88:89], v[42:43], v[42:43], v[88:89]
	v_pk_fma_f32 v[88:89], v[44:45], v[44:45], v[88:89]
	v_pk_fma_f32 v[88:89], v[46:47], v[46:47], v[88:89]
	v_pk_fma_f32 v[88:89], v[48:49], v[48:49], v[88:89]
	v_pk_fma_f32 v[88:89], v[50:51], v[50:51], v[88:89]
	v_pk_fma_f32 v[88:89], v[52:53], v[52:53], v[88:89]
	v_pk_fma_f32 v[88:89], v[54:55], v[54:55], v[88:89]
	v_add_u32_e32 v19, 0x400000, v19
	v_cvt_pk_bf16_f32 v40, v40, v41
	v_cvt_pk_bf16_f32 v41, v42, v43
	v_cvt_pk_bf16_f32 v42, v44, v45
	v_cvt_pk_bf16_f32 v43, v46, v47
	global_store_dwordx4 v19, v[40:43], s[4:5]
	v_cvt_pk_bf16_f32 v48, v48, v49
	v_cvt_pk_bf16_f32 v49, v50, v51
	v_cvt_pk_bf16_f32 v50, v52, v53
	v_cvt_pk_bf16_f32 v51, v54, v55
	global_store_dwordx4 v19, v[48:51], s[4:5] offset:1024
	v_add_f32_e32 v90, v88, v89
	v_add_u32_e32 v20, 0x2000, v20
	s_nop 1
	v_add_f32_dpp v90, v90, v90 quad_perm:[1,0,3,2] row_mask:0xf bank_mask:0xf
	s_nop 1
	v_add_f32_dpp v90, v90, v90 quad_perm:[2,3,0,1] row_mask:0xf bank_mask:0xf
	s_nop 1
	v_add_f32_dpp v90, v90, v90 row_half_mirror row_mask:0xf bank_mask:0xf
	s_nop 1
	v_add_f32_dpp v90, v90, v90 row_mirror row_mask:0xf bank_mask:0xf
	s_nop 1
	v_add_f32_dpp v90, v90, v90 row_bcast:15 row_mask:0xa bank_mask:0xf
	s_nop 1
	v_add_f32_dpp v90, v90, v90 row_bcast:31 row_mask:0xc bank_mask:0xf
	v_fmamk_f32 v91, v90, 0x3a800000, v92
	v_rsq_f32_e32 v91, v91
	s_mov_b64 exec, s[12:13]
	global_store_dword v20, v91, s[4:5]
	s_mov_b64 exec, -1
	v_add_u32_e32 v18, 0x800000, v18
	global_load_dwordx4 v[40:43], v18, s[10:11]
	global_load_dwordx4 v[44:47], v18, s[10:11] offset:16
	global_load_dwordx4 v[48:51], v18, s[10:11] offset:2048
	global_load_dwordx4 v[52:55], v18, s[10:11] offset:2064
	s_waitcnt vmcnt(21)
	v_pk_mul_f32 v[88:89], v[56:57], v[56:57]
	v_pk_fma_f32 v[88:89], v[58:59], v[58:59], v[88:89]
	v_pk_fma_f32 v[88:89], v[60:61], v[60:61], v[88:89]
	v_pk_fma_f32 v[88:89], v[62:63], v[62:63], v[88:89]
	v_pk_fma_f32 v[88:89], v[64:65], v[64:65], v[88:89]
	v_pk_fma_f32 v[88:89], v[66:67], v[66:67], v[88:89]
	v_pk_fma_f32 v[88:89], v[68:69], v[68:69], v[88:89]
	v_pk_fma_f32 v[88:89], v[70:71], v[70:71], v[88:89]
	v_add_u32_e32 v19, 0x400000, v19
	v_cvt_pk_bf16_f32 v56, v56, v57
	v_cvt_pk_bf16_f32 v57, v58, v59
	v_cvt_pk_bf16_f32 v58, v60, v61
	v_cvt_pk_bf16_f32 v59, v62, v63
	global_store_dwordx4 v19, v[56:59], s[4:5]
	v_cvt_pk_bf16_f32 v64, v64, v65
	v_cvt_pk_bf16_f32 v65, v66, v67
	v_cvt_pk_bf16_f32 v66, v68, v69
	v_cvt_pk_bf16_f32 v67, v70, v71
	global_store_dwordx4 v19, v[64:67], s[4:5] offset:1024
	v_add_f32_e32 v90, v88, v89
	v_add_u32_e32 v20, 0x2000, v20
	s_nop 1
	v_add_f32_dpp v90, v90, v90 quad_perm:[1,0,3,2] row_mask:0xf bank_mask:0xf
	s_nop 1
	v_add_f32_dpp v90, v90, v90 quad_perm:[2,3,0,1] row_mask:0xf bank_mask:0xf
	s_nop 1
	v_add_f32_dpp v90, v90, v90 row_half_mirror row_mask:0xf bank_mask:0xf
	s_nop 1
	v_add_f32_dpp v90, v90, v90 row_mirror row_mask:0xf bank_mask:0xf
	s_nop 1
	v_add_f32_dpp v90, v90, v90 row_bcast:15 row_mask:0xa bank_mask:0xf
	s_nop 1
	v_add_f32_dpp v90, v90, v90 row_bcast:31 row_mask:0xc bank_mask:0xf
	v_fmamk_f32 v91, v90, 0x3a800000, v92
	v_rsq_f32_e32 v91, v91
	s_mov_b64 exec, s[12:13]
	global_store_dword v20, v91, s[4:5]
	s_mov_b64 exec, -1
	v_add_u32_e32 v18, 0x800000, v18
	global_load_dwordx4 v[56:59], v18, s[10:11]
	global_load_dwordx4 v[60:63], v18, s[10:11] offset:16
	global_load_dwordx4 v[64:67], v18, s[10:11] offset:2048
	global_load_dwordx4 v[68:71], v18, s[10:11] offset:2064
	s_waitcnt vmcnt(21)
; #define PIN(i) karg_ptr(8 * (i))
; __global__ void __launch_bounds__(512, 2) fwd_megakernel(Params P) {
;     ...
;         for (int row0 = gw; row0 < MTOK; row0 += 4 * NGW) {
;             f32x4 xa[4][2][2];
; #pragma unroll
;             for (int k = 0; k < 4; ++k) { const int row = row0 + k * NGW; const float* xr = row < 16384 ? PIN(I_XP) + (size_t)row * DM : PIN(I_XS) + (size_t)(row - 16384) * DM;
; #pragma unroll
;                 for (int j = 0; j < 2; ++j) { xa[k][j][0] = *(const f32x4*)(xr + 8 * lane + 512 * j); xa[k][j][1] = *(const f32x4*)(xr + 8 * lane + 512 * j + 4); } }
; #pragma unroll
;             for (int k = 0; k < 4; ++k) { const int row = row0 + k * NGW; float s = 0.f;
; #pragma unroll
;                 for (int j = 0; j < 2; ++j) { const f32x4 a = xa[k][j][0], b = xa[k][j][1];
;                     s += (a[0] * a[0] + a[1] * a[1]) + (a[2] * a[2] + a[3] * a[3]) + (b[0] * b[0] + b[1] * b[1]) + (b[2] * b[2] + b[3] * b[3]);
;                     u32x4 o; o.x = pk2(a[0], a[1]); o.y = pk2(a[2], a[3]); o.z = pk2(b[0], b[1]); o.w = pk2(b[2], b[3]); *(u32x4*)(XB + (size_t)row * DM + 8 * lane + 512 * j) = o; }
;                 s = wave_sum(s); if (lane == 0) rstdA[row] = __builtin_amdgcn_rsqf(s * (1.0f / DM) + RMS_EPS); }
	v_pk_mul_f32 v[88:89], v[72:73], v[72:73]
	v_pk_fma_f32 v[88:89], v[74:75], v[74:75], v[88:89]
	v_pk_fma_f32 v[88:89], v[76:77], v[76:77], v[88:89]
	v_pk_fma_f32 v[88:89], v[78:79], v[78:79], v[88:89]
	v_pk_fma_f32 v[88:89], v[80:81], v[80:81], v[88:89]
	v_pk_fma_f32 v[88:89], v[82:83], v[82:83], v[88:89]
	v_pk_fma_f32 v[88:89], v[84:85], v[84:85], v[88:89]
	v_pk_fma_f32 v[88:89], v[86:87], v[86:87], v[88:89]
	v_add_u32_e32 v19, 0x400000, v19
	v_cvt_pk_bf16_f32 v72, v72, v73
	v_cvt_pk_bf16_f32 v73, v74, v75
	v_cvt_pk_bf16_f32 v74, v76, v77
	v_cvt_pk_bf16_f32 v75, v78, v79
	global_store_dwordx4 v19, v[72:75], s[4:5]
	v_cvt_pk_bf16_f32 v80, v80, v81
	v_cvt_pk_bf16_f32 v81, v82, v83
	v_cvt_pk_bf16_f32 v82, v84, v85
	v_cvt_pk_bf16_f32 v83, v86, v87
	global_store_dwordx4 v19, v[80:83], s[4:5] offset:1024
	v_add_f32_e32 v90, v88, v89
	v_add_u32_e32 v20, 0x2000, v20
	s_nop 1
	v_add_f32_dpp v90, v90, v90 quad_perm:[1,0,3,2] row_mask:0xf bank_mask:0xf
	s_nop 1
	v_add_f32_dpp v90, v90, v90 quad_perm:[2,3,0,1] row_mask:0xf bank_mask:0xf
	s_nop 1
	v_add_f32_dpp v90, v90, v90 row_half_mirror row_mask:0xf bank_mask:0xf
	s_nop 1
	v_add_f32_dpp v90, v90, v90 row_mirror row_mask:0xf bank_mask:0xf
	s_nop 1
	v_add_f32_dpp v90, v90, v90 row_bcast:15 row_mask:0xa bank_mask:0xf
	s_nop 1
	v_add_f32_dpp v90, v90, v90 row_bcast:31 row_mask:0xc bank_mask:0xf
	v_fmamk_f32 v91, v90, 0x3a800000, v92
	v_rsq_f32_e32 v91, v91
	s_mov_b64 exec, s[12:13]
	global_store_dword v20, v91, s[4:5]
	s_mov_b64 exec, -1
	v_add_u32_e32 v18, 0x800000, v18
	global_load_dwordx4 v[72:75], v18, s[10:11]
	global_load_dwordx4 v[76:79], v18, s[10:11] offset:16
	global_load_dwordx4 v[80:83], v18, s[10:11] offset:2048
	global_load_dwordx4 v[84:87], v18, s[10:11] offset:2064
	s_waitcnt vmcnt(21)
	v_pk_mul_f32 v[88:89], v[24:25], v[24:25]
	v_pk_fma_f32 v[88:89], v[26:27], v[26:27], v[88:89]
	v_pk_fma_f32 v[88:89], v[28:29], v[28:29], v[88:89]
	v_pk_fma_f32 v[88:89], v[30:31], v[30:31], v[88:89]
	v_pk_fma_f32 v[88:89], v[32:33], v[32:33], v[88:89]
	v_pk_fma_f32 v[88:89], v[34:35], v[34:35], v[88:89]
	v_pk_fma_f32 v[88:89], v[36:37], v[36:37], v[88:89]
	v_pk_fma_f32 v[88:89], v[38:39], v[38:39], v[88:89]
	v_add_u32_e32 v19, 0x400000, v19
	v_cvt_pk_bf16_f32 v24, v24, v25
	v_cvt_pk_bf16_f32 v25, v26, v27
	v_cvt_pk_bf16_f32 v26, v28, v29
	v_cvt_pk_bf16_f32 v27, v30, v31
	global_store_dwordx4 v19, v[24:27], s[4:5]
	v_cvt_pk_bf16_f32 v32, v32, v33
	v_cvt_pk_bf16_f32 v33, v34, v35
	v_cvt_pk_bf16_f32 v34, v36, v37
	v_cvt_pk_bf16_f32 v35, v38, v39
	global_store_dwordx4 v19, v[32:35], s[4:5] offset:1024
	v_add_f32_e32 v90, v88, v89
	v_add_u32_e32 v20, 0x2000, v20
	s_nop 1
	v_add_f32_dpp v90, v90, v90 quad_perm:[1,0,3,2] row_mask:0xf bank_mask:0xf
	s_nop 1
	v_add_f32_dpp v90, v90, v90 quad_perm:[2,3,0,1] row_mask:0xf bank_mask:0xf
	s_nop 1
	v_add_f32_dpp v90, v90, v90 row_half_mirror row_mask:0xf bank_mask:0xf
	s_nop 1
	v_add_f32_dpp v90, v90, v90 row_mirror row_mask:0xf bank_mask:0xf
	s_nop 1
	v_add_f32_dpp v90, v90, v90 row_bcast:15 row_mask:0xa bank_mask:0xf
	s_nop 1
	v_add_f32_dpp v90, v90, v90 row_bcast:31 row_mask:0xc bank_mask:0xf
	v_fmamk_f32 v91, v90, 0x3a800000, v92
	v_rsq_f32_e32 v91, v91
	s_mov_b64 exec, s[12:13]
	global_store_dword v20, v91, s[4:5]
	s_mov_b64 exec, -1
	s_waitcnt vmcnt(17)
; #define PIN(i) karg_ptr(8 * (i))
; __global__ void __launch_bounds__(512, 2) fwd_megakernel(Params P) {
;     ...
;         for (int row0 = gw; row0 < MTOK; row0 += 4 * NGW) {
;             f32x4 xa[4][2][2];
; #pragma unroll
;             for (int k = 0; k < 4; ++k) { const int row = row0 + k * NGW; const float* xr = row < 16384 ? PIN(I_XP) + (size_t)row * DM : PIN(I_XS) + (size_t)(row - 16384) * DM;
; #pragma unroll
;                 for (int j = 0; j < 2; ++j) { xa[k][j][0] = *(const f32x4*)(xr + 8 * lane + 512 * j); xa[k][j][1] = *(const f32x4*)(xr + 8 * lane + 512 * j + 4); } }
; #pragma unroll
;             for (int k = 0; k < 4; ++k) { const int row = row0 + k * NGW; float s = 0.f;
; #pragma unroll
;                 for (int j = 0; j < 2; ++j) { const f32x4 a = xa[k][j][0], b = xa[k][j][1];
;                     s += (a[0] * a[0] + a[1] * a[1]) + (a[2] * a[2] + a[3] * a[3]) + (b[0] * b[0] + b[1] * b[1]) + (b[2] * b[2] + b[3] * b[3]);
;                     u32x4 o; o.x = pk2(a[0], a[1]); o.y = pk2(a[2], a[3]); o.z = pk2(b[0], b[1]); o.w = pk2(b[2], b[3]); *(u32x4*)(XB + (size_t)row * DM + 8 * lane + 512 * j) = o; }
;                 s = wave_sum(s); if (lane == 0) rstdA[row] = __builtin_amdgcn_rsqf(s * (1.0f / DM) + RMS_EPS); }
	v_pk_mul_f32 v[88:89], v[40:41], v[40:41]
	v_pk_fma_f32 v[88:89], v[42:43], v[42:43], v[88:89]
	v_pk_fma_f32 v[88:89], v[44:45], v[44:45], v[88:89]
	v_pk_fma_f32 v[88:89], v[46:47], v[46:47], v[88:89]
	v_pk_fma_f32 v[88:89], v[48:49], v[48:49], v[88:89]
	v_pk_fma_f32 v[88:89], v[50:51], v[50:51], v[88:89]
	v_pk_fma_f32 v[88:89], v[52:53], v[52:53], v[88:89]
	v_pk_fma_f32 v[88:89], v[54:55], v[54:55], v[88:89]
	v_add_u32_e32 v19, 0x400000, v19
	v_cvt_pk_bf16_f32 v40, v40, v41
	v_cvt_pk_bf16_f32 v41, v42, v43
	v_cvt_pk_bf16_f32 v42, v44, v45
	v_cvt_pk_bf16_f32 v43, v46, v47
	global_store_dwordx4 v19, v[40:43], s[4:5]
	v_cvt_pk_bf16_f32 v48, v48, v49
	v_cvt_pk_bf16_f32 v49, v50, v51
	v_cvt_pk_bf16_f32 v50, v52, v53
	v_cvt_pk_bf16_f32 v51, v54, v55
	global_store_dwordx4 v19, v[48:51], s[4:5] offset:1024
	v_add_f32_e32 v90, v88, v89
	v_add_u32_e32 v20, 0x2000, v20
	s_nop 1
	v_add_f32_dpp v90, v90, v90 quad_perm:[1,0,3,2] row_mask:0xf bank_mask:0xf
	s_nop 1
	v_add_f32_dpp v90, v90, v90 quad_perm:[2,3,0,1] row_mask:0xf bank_mask:0xf
	s_nop 1
	v_add_f32_dpp v90, v90, v90 row_half_mirror row_mask:0xf bank_mask:0xf
	s_nop 1
	v_add_f32_dpp v90, v90, v90 row_mirror row_mask:0xf bank_mask:0xf
	s_nop 1
	v_add_f32_dpp v90, v90, v90 row_bcast:15 row_mask:0xa bank_mask:0xf
	s_nop 1
	v_add_f32_dpp v90, v90, v90 row_bcast:31 row_mask:0xc bank_mask:0xf
	v_fmamk_f32 v91, v90, 0x3a800000, v92
	v_rsq_f32_e32 v91, v91
	s_mov_b64 exec, s[12:13]
	global_store_dword v20, v91, s[4:5]
	s_mov_b64 exec, -1
	s_waitcnt vmcnt(13)
	v_pk_mul_f32 v[88:89], v[56:57], v[56:57]
	v_pk_fma_f32 v[88:89], v[58:59], v[58:59], v[88:89]
	v_pk_fma_f32 v[88:89], v[60:61], v[60:61], v[88:89]
	v_pk_fma_f32 v[88:89], v[62:63], v[62:63], v[88:89]
	v_pk_fma_f32 v[88:89], v[64:65], v[64:65], v[88:89]
	v_pk_fma_f32 v[88:89], v[66:67], v[66:67], v[88:89]
	v_pk_fma_f32 v[88:89], v[68:69], v[68:69], v[88:89]
	v_pk_fma_f32 v[88:89], v[70:71], v[70:71], v[88:89]
	v_add_u32_e32 v19, 0x400000, v19
	v_cvt_pk_bf16_f32 v56, v56, v57
	v_cvt_pk_bf16_f32 v57, v58, v59
	v_cvt_pk_bf16_f32 v58, v60, v61
	v_cvt_pk_bf16_f32 v59, v62, v63
	global_store_dwordx4 v19, v[56:59], s[4:5]
	v_cvt_pk_bf16_f32 v64, v64, v65
	v_cvt_pk_bf16_f32 v65, v66, v67
	v_cvt_pk_bf16_f32 v66, v68, v69
	v_cvt_pk_bf16_f32 v67, v70, v71
	global_store_dwordx4 v19, v[64:67], s[4:5] offset:1024
	v_add_f32_e32 v90, v88, v89
	v_add_u32_e32 v20, 0x2000, v20
	s_nop 1
	v_add_f32_dpp v90, v90, v90 quad_perm:[1,0,3,2] row_mask:0xf bank_mask:0xf
	s_nop 1
	v_add_f32_dpp v90, v90, v90 quad_perm:[2,3,0,1] row_mask:0xf bank_mask:0xf
	s_nop 1
	v_add_f32_dpp v90, v90, v90 row_half_mirror row_mask:0xf bank_mask:0xf
	s_nop 1
	v_add_f32_dpp v90, v90, v90 row_mirror row_mask:0xf bank_mask:0xf
	s_nop 1
	v_add_f32_dpp v90, v90, v90 row_bcast:15 row_mask:0xa bank_mask:0xf
	s_nop 1
	v_add_f32_dpp v90, v90, v90 row_bcast:31 row_mask:0xc bank_mask:0xf
	v_fmamk_f32 v91, v90, 0x3a800000, v92
	v_rsq_f32_e32 v91, v91
	s_mov_b64 exec, s[12:13]
	global_store_dword v20, v91, s[4:5]
	s_mov_b64 exec, -1
	s_waitcnt vmcnt(9)
	v_pk_mul_f32 v[88:89], v[72:73], v[72:73]
	v_pk_fma_f32 v[88:89], v[74:75], v[74:75], v[88:89]
	v_pk_fma_f32 v[88:89], v[76:77], v[76:77], v[88:89]
	v_pk_fma_f32 v[88:89], v[78:79], v[78:79], v[88:89]
	v_pk_fma_f32 v[88:89], v[80:81], v[80:81], v[88:89]
	v_pk_fma_f32 v[88:89], v[82:83], v[82:83], v[88:89]
	v_pk_fma_f32 v[88:89], v[84:85], v[84:85], v[88:89]
	v_pk_fma_f32 v[88:89], v[86:87], v[86:87], v[88:89]
	v_add_u32_e32 v19, 0x400000, v19
	v_cvt_pk_bf16_f32 v72, v72, v73
	v_cvt_pk_bf16_f32 v73, v74, v75
	v_cvt_pk_bf16_f32 v74, v76, v77
	v_cvt_pk_bf16_f32 v75, v78, v79
	global_store_dwordx4 v19, v[72:75], s[4:5]
	v_cvt_pk_bf16_f32 v80, v80, v81
	v_cvt_pk_bf16_f32 v81, v82, v83
	v_cvt_pk_bf16_f32 v82, v84, v85
	v_cvt_pk_bf16_f32 v83, v86, v87
	global_store_dwordx4 v19, v[80:83], s[4:5] offset:1024
	v_add_f32_e32 v90, v88, v89
	v_add_u32_e32 v20, 0x2000, v20
	s_nop 1
	v_add_f32_dpp v90, v90, v90 quad_perm:[1,0,3,2] row_mask:0xf bank_mask:0xf
	s_nop 1
	v_add_f32_dpp v90, v90, v90 quad_perm:[2,3,0,1] row_mask:0xf bank_mask:0xf
	s_nop 1
	v_add_f32_dpp v90, v90, v90 row_half_mirror row_mask:0xf bank_mask:0xf
	s_nop 1
	v_add_f32_dpp v90, v90, v90 row_mirror row_mask:0xf bank_mask:0xf
	s_nop 1
	v_add_f32_dpp v90, v90, v90 row_bcast:15 row_mask:0xa bank_mask:0xf
	s_nop 1
	v_add_f32_dpp v90, v90, v90 row_bcast:31 row_mask:0xc bank_mask:0xf
	v_fmamk_f32 v91, v90, 0x3a800000, v92
	v_rsq_f32_e32 v91, v91
	s_mov_b64 exec, s[12:13]
	global_store_dword v20, v91, s[4:5]
	s_mov_b64 exec, -1
